# attention hot heads: permlane wait gap filled with two ready MFMAs (s_nop 1 removed), It-B m0 write hoisted above the barrier (s_nop 0 removed)
# baseline (speedup 1.0000x reference)
.Lattn1_nomask:
	s_add_i32 s9, s78, 0x10000
	s_and_b32 s33, s9, 0x18000
	s_and_b32 s76, s78, 0x18000
	v_add_u32_e32 v239, s33, v237
	v_add_u32_e32 v250, v239, v228
	ds_read_b128 v[128:131], v250 offset:16384
	ds_read_b128 v[132:135], v250 offset:20480
	ds_read_b128 v[136:139], v250 offset:24576
	ds_read_b128 v[140:143], v250 offset:28672
	v_add_u32_e32 v251, s76, v235
	v_add_u32_e32 v250, v251, v228
	ds_read_b128 v[144:147], v250
	ds_read_b128 v[148:151], v250 offset:4096
	v_add_u32_e32 v250, v251, v231
	ds_read_b128 v[152:155], v250
	ds_read_b128 v[156:159], v250 offset:4096
	s_add_i32 s0, s74, s38
	s_addk_i32 s0, 0xc0
	s_mul_i32 s0, s0, s14
	s_lshl_b32 s92, s46, 1
	s_add_i32 s0, s0, s92
	s_addk_i32 s0, 0x1c00
	s_add_u32 s98, s82, s0
	s_addc_u32 s99, s83, 0
	s_add_i32 s0, s78, 0x8000
	s_and_b32 s0, s0, 0x18000
	s_add_i32 s0, s5, s0
	s_mov_b32 m0, s0
	s_nop 0
	global_load_lds_dwordx4 v244, s[98:99]
	s_add_i32 m0, s0, 0x2000
	s_add_u32 s98, s98, 0x80
	s_addc_u32 s99, s99, 0
	global_load_lds_dwordx4 v244, s[98:99]
	s_lshl_b32 s1, s17, 13
	s_add_u32 s98, s40, s1
	s_addc_u32 s99, s41, 0
	s_add_i32 m0, s0, 0x4000
	s_nop 0
	global_load_lds_dwordx4 v245, s[98:99]
	s_add_i32 m0, s0, 0x6000
	s_add_u32 s98, s98, 0x80000
	s_addc_u32 s99, s99, 0
	global_load_lds_dwordx4 v245, s[98:99]
	v_max3_f32 v246, v64, v65, v66
	v_max3_f32 v247, v72, v73, v74
	v_max3_f32 v248, v80, v81, v82
	v_max3_f32 v249, v88, v89, v90
	v_max3_f32 v246, v246, v67, v68
	v_max3_f32 v247, v247, v75, v76
	v_max3_f32 v248, v248, v83, v84
	v_max3_f32 v249, v249, v91, v92
	s_waitcnt lgkmcnt(7)
	v_mfma_f32_32x32x16_bf16 v[0:15], v[128:131], v[96:99], v[0:15]
	v_max3_f32 v246, v246, v69, v70
	v_max3_f32 v247, v247, v77, v78
	v_max3_f32 v248, v248, v85, v86
	v_max3_f32 v249, v249, v93, v94
	v_max3_f32 v246, v246, v71, v247
	v_max3_f32 v247, v248, v87, v249
	s_waitcnt lgkmcnt(6)
	v_mfma_f32_32x32x16_bf16 v[48:63], v[132:135], v[96:99], v[48:63]
	v_max3_f32 v246, v246, v79, v95
	v_max3_f32 v246, v246, v247, v247
	v_mov_b32_e32 v247, v246
	s_waitcnt lgkmcnt(5)
	v_mfma_f32_32x32x16_bf16 v[32:47], v[136:139], v[96:99], v[32:47]
	s_waitcnt lgkmcnt(4)
	v_mfma_f32_32x32x16_bf16 v[16:31], v[140:143], v[96:99], v[16:31]
	v_permlane32_swap_b32_e32 v246, v247
	v_max3_f32 v246, v246, v247, v247
	v_max_f32_e32 v251, v212, v246
	v_sub_f32_e32 v247, v212, v251
	v_exp_f32_e32 v250, v247
	v_add_f32_e32 v247, 0x41000000, v212
	v_cmp_gt_f32_e32 vcc, v246, v247
	s_cmp_eq_u64 vcc, 0
	v_mul_f32_e32 v246, v100, v250
	s_cselect_b64 s[0:1], -1, 0
	v_cndmask_b32_e64 v194, v246, v100, s[0:1]
	v_cndmask_b32_e64 v212, v251, v212, s[0:1]
	v_sub_f32_e32 v140, v92, v212
	v_sub_f32_e32 v141, v93, v212
	v_sub_f32_e32 v138, v90, v212
	v_sub_f32_e32 v139, v91, v212
	s_waitcnt lgkmcnt(3)
	v_mfma_f32_32x32x16_bf16 v[96:111], v[144:147], v[160:163], 0
	v_sub_f32_e32 v142, v94, v212
	v_sub_f32_e32 v143, v95, v212
	v_sub_f32_e32 v92, v80, v212
	v_sub_f32_e32 v93, v81, v212
	v_sub_f32_e32 v128, v82, v212
	v_sub_f32_e32 v129, v83, v212
	s_waitcnt lgkmcnt(2)
	v_mfma_f32_32x32x16_bf16 v[112:127], v[148:151], v[160:163], 0
	v_sub_f32_e32 v130, v68, v212
	v_sub_f32_e32 v131, v69, v212
	v_sub_f32_e32 v90, v64, v212
	v_sub_f32_e32 v91, v65, v212
	v_sub_f32_e32 v132, v84, v212
	v_sub_f32_e32 v133, v85, v212
	s_waitcnt lgkmcnt(1)
	v_mfma_f32_32x32x16_bf16 v[96:111], v[152:155], v[164:167], v[96:111]
	v_sub_f32_e32 v94, v66, v212
	v_sub_f32_e32 v95, v67, v212
	v_sub_f32_e32 v134, v86, v212
	v_sub_f32_e32 v135, v87, v212
	v_sub_f32_e32 v136, v88, v212
	v_sub_f32_e32 v137, v89, v212
	s_waitcnt lgkmcnt(0)
	v_mfma_f32_32x32x16_bf16 v[112:127], v[156:159], v[164:167], v[112:127]
	v_sub_f32_e32 v144, v70, v212
	v_sub_f32_e32 v145, v71, v212
	v_sub_f32_e32 v148, v74, v212
	v_sub_f32_e32 v149, v75, v212
	v_sub_f32_e32 v150, v76, v212
	v_sub_f32_e32 v151, v77, v212
	v_sub_f32_e32 v146, v72, v212
	v_sub_f32_e32 v147, v73, v212
	v_sub_f32_e32 v152, v78, v212
	v_sub_f32_e32 v153, v79, v212
	v_mov_b32_e32 v68, v250
	s_branch .Lattn_body_1

.LBB0_836:
	s_add_i32 s79, s10, 2
	s_cmp_ge_u32 s79, s8
	s_cselect_b64 s[76:77], -1, 0
	s_and_b64 vcc, exec, s[76:77]
	s_add_i32 s0, s74, s38
	s_addk_i32 s0, 0x100
	s_mul_i32 s0, s0, s14
	s_lshl_b32 s92, s46, 1
	s_add_i32 s0, s0, s92
	s_addk_i32 s0, 0x1c00
	s_add_u32 s98, s82, s0
	s_addc_u32 s99, s83, 0
	s_lshl_b32 s1, s17, 13
	s_add_u32 s0, s40, s1
	s_addc_u32 s1, s41, 0
	s_add_u32 s0, s0, 0x80
	s_addc_u32 s1, s1, 0
	s_add_i32 s32, s5, s33
	s_mov_b32 m0, s32
	s_waitcnt vmcnt(2)
	s_barrier
	s_cbranch_vccnz .LBB0_838
	global_load_lds_dwordx4 v244, s[98:99]
	s_add_i32 m0, s32, 0x2000
	s_add_u32 s98, s98, 0x80
	s_addc_u32 s99, s99, 0
	global_load_lds_dwordx4 v244, s[98:99]
	s_add_i32 m0, s32, 0x4000
	s_nop 0
	global_load_lds_dwordx4 v245, s[0:1]
	s_add_i32 m0, s32, 0x6000
	s_add_u32 s0, s0, 0x80000
	s_addc_u32 s1, s1, 0
	global_load_lds_dwordx4 v245, s[0:1]

.LBB0_840:
	s_add_i32 s0, s78, 0xffff8000
	s_and_b32 s10, s0, 0x18000
	v_add_u32_e32 v76, s10, v237
	v_add_u32_e32 v76, v76, v228
	ds_read_b128 v[80:83], v76 offset:16384
	ds_read_b128 v[84:87], v76 offset:20480
	ds_read_b128 v[88:91], v76 offset:24576
	ds_read_b128 v[92:95], v76 offset:28672
	v_max3_f32 v68, v96, v97, v98
	v_max3_f32 v70, v104, v105, v106
	v_max3_f32 v71, v112, v113, v114
	v_max3_f32 v72, v120, v121, v122
	v_max3_f32 v68, v68, v99, v100
	v_max3_f32 v70, v70, v107, v108
	v_max3_f32 v71, v71, v115, v116
	v_max3_f32 v72, v72, v123, v124
	s_waitcnt lgkmcnt(3)
	v_mfma_f32_32x32x16_bf16 v[0:15], v[80:83], v[64:67], v[0:15]
	v_max3_f32 v68, v68, v101, v102
	v_max3_f32 v70, v70, v109, v110
	v_max3_f32 v71, v71, v117, v118
	v_max3_f32 v72, v72, v125, v126
	s_xor_b32 s33, s10, 0x10000
	v_max3_f32 v68, v68, v103, v70
	v_max3_f32 v70, v71, v119, v72
	s_waitcnt lgkmcnt(2)
	v_mfma_f32_32x32x16_bf16 v[48:63], v[84:87], v[64:67], v[48:63]
	v_max3_f32 v68, v68, v111, v127
	v_max3_f32 v68, v68, v70, v70
	v_mov_b32_e32 v70, v68
	s_waitcnt lgkmcnt(1)
	v_mfma_f32_32x32x16_bf16 v[32:47], v[88:91], v[64:67], v[32:47]
	s_waitcnt lgkmcnt(0)
	v_mfma_f32_32x32x16_bf16 v[16:31], v[92:95], v[64:67], v[16:31]
	v_permlane32_swap_b32_e32 v68, v70
	v_max3_f32 v68, v68, v70, v70
	v_max_f32_e32 v141, v212, v68
	v_sub_f32_e32 v70, v212, v141
	v_exp_f32_e32 v140, v70
	v_add_f32_e32 v70, 0x41000000, v212
	v_cmp_gt_f32_e32 vcc, v68, v70
	s_cmp_eq_u64 vcc, 0
	v_mul_f32_e32 v68, v69, v140
	s_cselect_b64 s[0:1], -1, 0
	v_cndmask_b32_e64 v194, v68, v69, s[0:1]
	v_add_u32_e32 v182, s10, v237
	v_add_u32_e32 v158, s33, v235
	v_add_u32_e32 v88, v158, v231
	v_add_u32_e32 v150, v182, v231
	v_add_u32_e32 v159, v158, v230
	v_cndmask_b32_e64 v212, v141, v212, s[0:1]
	v_add_u32_e32 v141, v182, v230
	v_sub_f32_e32 v180, v102, v212
	v_sub_f32_e32 v181, v103, v212
	v_sub_f32_e32 v116, v116, v212
	v_sub_f32_e32 v117, v117, v212
	v_sub_f32_e32 v108, v108, v212
	v_sub_f32_e32 v109, v109, v212
	v_sub_f32_e32 v124, v124, v212
	v_sub_f32_e32 v125, v125, v212
	v_exp_f32_e32 v116, v116
	v_exp_f32_e32 v117, v117
	v_exp_f32_e32 v108, v108
	v_exp_f32_e32 v124, v124
	v_exp_f32_e32 v109, v109
	v_add_u32_e32 v68, v158, v228
	v_add_u32_e32 v158, v158, v229
	v_exp_f32_e32 v125, v125
	v_sub_f32_e32 v114, v114, v212
	v_sub_f32_e32 v115, v115, v212
	v_sub_f32_e32 v118, v118, v212
	v_sub_f32_e32 v119, v119, v212
	v_sub_f32_e32 v122, v122, v212
	v_sub_f32_e32 v123, v123, v212
	v_sub_f32_e32 v110, v110, v212
	v_sub_f32_e32 v111, v111, v212
	ds_read_b128 v[64:67], v68
	ds_read_b128 v[80:83], v68 offset:4096
	ds_read_b128 v[84:87], v88
	ds_read_b128 v[142:145], v88 offset:4096
	v_sub_f32_e32 v126, v126, v212
	v_sub_f32_e32 v127, v127, v212
	v_sub_f32_e32 v106, v106, v212
	v_sub_f32_e32 v107, v107, v212
	v_exp_f32_e32 v114, v114
	v_exp_f32_e32 v115, v115
	v_exp_f32_e32 v118, v118
	s_waitcnt lgkmcnt(0)
	v_mfma_f32_32x32x16_bf16 v[64:79], v[64:67], v[160:163], 0
	v_exp_f32_e32 v119, v119
	v_exp_f32_e32 v122, v122
	v_exp_f32_e32 v123, v123
	v_exp_f32_e32 v110, v110
	v_exp_f32_e32 v126, v126
	v_exp_f32_e32 v111, v111
	v_exp_f32_e32 v127, v127
	v_mfma_f32_32x32x16_bf16 v[64:79], v[84:87], v[164:167], v[64:79]
	v_sub_f32_e32 v104, v104, v212
	v_sub_f32_e32 v105, v105, v212
	v_sub_f32_e32 v112, v112, v212
	v_sub_f32_e32 v113, v113, v212
	v_sub_f32_e32 v120, v120, v212
	v_sub_f32_e32 v121, v121, v212
	v_cvt_pk_bf16_f32 v183, v118, v119
	v_exp_f32_e32 v112, v112
	v_exp_f32_e32 v113, v113
	v_exp_f32_e32 v120, v120
	v_mfma_f32_32x32x16_bf16 v[80:95], v[80:83], v[160:163], 0
	v_exp_f32_e32 v121, v121
	v_cvt_pk_bf16_f32 v186, v108, v109
	v_cvt_pk_bf16_f32 v187, v110, v111
	v_mfma_f32_32x32x16_bf16 v[80:95], v[142:145], v[164:167], v[80:95]
	ds_read_b128 v[142:145], v150 offset:16384
	ds_read_b128 v[146:149], v150 offset:20480
	s_waitcnt lgkmcnt(0)
	v_mfma_f32_32x32x16_bf16 v[0:15], v[142:145], v[136:139], v[0:15]
	ds_read_b128 v[142:145], v150 offset:24576
	ds_read_b128 v[150:153], v150 offset:28672
	ds_read_b128 v[154:157], v159
	ds_read_b128 v[176:179], v159 offset:4096
	v_mfma_f32_32x32x16_bf16 v[48:63], v[146:149], v[136:139], v[48:63]
	ds_read_b128 v[146:149], v158
	ds_read_b128 v[238:241], v158 offset:4096
	v_sub_f32_e32 v158, v96, v212
	v_sub_f32_e32 v159, v97, v212
	s_waitcnt lgkmcnt(0)
	v_mfma_f32_32x32x16_bf16 v[32:47], v[142:145], v[136:139], v[32:47]
	v_sub_f32_e32 v142, v98, v212
	v_sub_f32_e32 v143, v99, v212
	v_sub_f32_e32 v144, v100, v212
	v_sub_f32_e32 v145, v101, v212
	ds_read_b128 v[96:99], v141 offset:16384
	ds_read_b128 v[100:103], v141 offset:20480
	s_waitcnt lgkmcnt(0)
	v_mfma_f32_32x32x16_bf16 v[0:15], v[96:99], v[132:135], v[0:15]
	ds_read_b128 v[96:99], v141 offset:24576
	v_mfma_f32_32x32x16_bf16 v[48:63], v[100:103], v[132:135], v[48:63]
	ds_read_b128 v[100:103], v141 offset:28672
	v_add_u32_e32 v141, v182, v229
	v_cvt_pk_bf16_f32 v182, v116, v117
	v_mfma_f32_32x32x16_bf16 v[16:31], v[150:153], v[136:139], v[16:31]
	v_exp_f32_e32 v138, v142
	v_exp_f32_e32 v139, v143
	v_exp_f32_e32 v142, v144
	v_exp_f32_e32 v143, v145
	v_exp_f32_e32 v144, v180
	v_exp_f32_e32 v145, v181
	v_exp_f32_e32 v136, v158
	s_waitcnt lgkmcnt(0)
	v_mfma_f32_32x32x16_bf16 v[32:47], v[96:99], v[132:135], v[32:47]
	ds_read_b128 v[96:99], v141 offset:16384
	v_exp_f32_e32 v137, v159
	v_cvt_pk_bf16_f32 v180, v112, v113
	v_cvt_pk_bf16_f32 v181, v114, v115
	v_add_f32_e32 v152, v136, v112
	v_add_f32_e32 v153, v137, v113
	v_mfma_f32_32x32x16_bf16 v[16:31], v[100:103], v[132:135], v[16:31]
	v_add_f32_e64 v100, v108, v124
	v_add_f32_e64 v101, v109, v125
	v_add_f32_e64 v102, v142, v116
	v_add_f32_e64 v103, v143, v117
	v_exp_f32_e32 v134, v106
	v_exp_f32_e32 v135, v107
	v_exp_f32_e32 v132, v104
	v_exp_f32_e32 v133, v105
	v_add_f32_e32 v106, v138, v114
	v_add_f32_e32 v107, v139, v115
	v_mfma_f32_32x32x16_bf16 v[64:79], v[154:157], v[168:171], v[64:79]
	v_add_f32_e64 v154, v102, v100
	v_add_f32_e64 v155, v103, v101
	ds_read_b128 v[100:103], v141 offset:20480
	v_add_f32_e64 v104, v134, v122
	v_add_f32_e64 v105, v135, v123
	v_add_f32_e32 v150, v132, v120
	v_add_f32_e32 v151, v133, v121
	v_add_f32_e32 v104, v106, v104
	v_add_f32_e32 v105, v107, v105
	v_cvt_pk_bf16_f32 v184, v132, v133
	v_cvt_pk_bf16_f32 v185, v134, v135
	v_mfma_f32_32x32x16_bf16 v[64:79], v[146:149], v[172:175], v[64:79]
	v_add_f32_e64 v146, v110, v126
	v_add_f32_e64 v147, v111, v127
	v_add_f32_e64 v148, v144, v118
	v_add_f32_e64 v149, v145, v119
	s_waitcnt lgkmcnt(0)
	v_mfma_f32_32x32x16_bf16 v[0:15], v[96:99], v[128:131], v[0:15]
	v_add_f32_e64 v98, v148, v146
	v_add_f32_e64 v99, v149, v147
	v_add_f32_e64 v96, v152, v150
	v_add_f32_e64 v97, v153, v151
	v_add_f32_e64 v98, v104, v98
	v_add_f32_e64 v99, v105, v99
	ds_read_b128 v[104:107], v141 offset:24576
	v_add_f32_e32 v96, v96, v154
	v_add_f32_e32 v97, v97, v155
	s_nop 0
	v_add_f32_e32 v96, v96, v97
	v_mfma_f32_32x32x16_bf16 v[48:63], v[100:103], v[128:131], v[48:63]
	ds_read_b128 v[100:103], v141 offset:28672
	v_add_f32_e32 v97, v98, v99
	v_add_f32_e32 v146, v96, v97
	v_cvt_pk_bf16_f32 v96, v136, v137
	v_cvt_pk_bf16_f32 v97, v138, v139
	v_cvt_pk_bf16_f32 v98, v142, v143
	v_cvt_pk_bf16_f32 v99, v144, v145
	v_mfma_f32_32x32x16_bf16 v[80:95], v[176:179], v[168:171], v[80:95]
	v_cvt_pk_bf16_f32 v176, v120, v121
	v_cvt_pk_bf16_f32 v177, v122, v123
	v_cvt_pk_bf16_f32 v178, v124, v125
	v_cvt_pk_bf16_f32 v179, v126, v127
	s_waitcnt lgkmcnt(0)
	v_mfma_f32_32x32x16_bf16 v[32:47], v[104:107], v[128:131], v[32:47]
	v_mfma_f32_32x32x16_bf16 v[16:31], v[100:103], v[128:131], v[16:31]
	v_add_f32_e32 v100, v194, v146
	v_mfma_f32_32x32x16_bf16 v[80:95], v[238:241], v[172:175], v[80:95]
	s_cbranch_vccz .LBB0_842
	v_pk_mul_f32 v[14:15], v[140:141], v[14:15] op_sel_hi:[0,1]
	v_pk_mul_f32 v[12:13], v[140:141], v[12:13] op_sel_hi:[0,1]
	v_pk_mul_f32 v[10:11], v[140:141], v[10:11] op_sel_hi:[0,1]
	v_pk_mul_f32 v[8:9], v[140:141], v[8:9] op_sel_hi:[0,1]
	v_pk_mul_f32 v[6:7], v[140:141], v[6:7] op_sel_hi:[0,1]
	v_pk_mul_f32 v[4:5], v[140:141], v[4:5] op_sel_hi:[0,1]
	v_pk_mul_f32 v[2:3], v[140:141], v[2:3] op_sel_hi:[0,1]
	v_pk_mul_f32 v[0:1], v[140:141], v[0:1] op_sel_hi:[0,1]
	v_pk_mul_f32 v[62:63], v[140:141], v[62:63] op_sel_hi:[0,1]
	v_pk_mul_f32 v[60:61], v[140:141], v[60:61] op_sel_hi:[0,1]
	v_pk_mul_f32 v[58:59], v[140:141], v[58:59] op_sel_hi:[0,1]
	v_pk_mul_f32 v[56:57], v[140:141], v[56:57] op_sel_hi:[0,1]
	v_pk_mul_f32 v[54:55], v[140:141], v[54:55] op_sel_hi:[0,1]
	v_pk_mul_f32 v[52:53], v[140:141], v[52:53] op_sel_hi:[0,1]
	v_pk_mul_f32 v[50:51], v[140:141], v[50:51] op_sel_hi:[0,1]
	v_pk_mul_f32 v[48:49], v[140:141], v[48:49] op_sel_hi:[0,1]
	v_pk_mul_f32 v[46:47], v[140:141], v[46:47] op_sel_hi:[0,1]
	v_pk_mul_f32 v[44:45], v[140:141], v[44:45] op_sel_hi:[0,1]
	v_pk_mul_f32 v[42:43], v[140:141], v[42:43] op_sel_hi:[0,1]
	v_pk_mul_f32 v[40:41], v[140:141], v[40:41] op_sel_hi:[0,1]
	v_pk_mul_f32 v[38:39], v[140:141], v[38:39] op_sel_hi:[0,1]
	v_pk_mul_f32 v[36:37], v[140:141], v[36:37] op_sel_hi:[0,1]
	v_pk_mul_f32 v[34:35], v[140:141], v[34:35] op_sel_hi:[0,1]
	v_pk_mul_f32 v[32:33], v[140:141], v[32:33] op_sel_hi:[0,1]
	v_pk_mul_f32 v[30:31], v[140:141], v[30:31] op_sel_hi:[0,1]
	v_pk_mul_f32 v[28:29], v[140:141], v[28:29] op_sel_hi:[0,1]
	v_pk_mul_f32 v[26:27], v[140:141], v[26:27] op_sel_hi:[0,1]
	v_pk_mul_f32 v[24:25], v[140:141], v[24:25] op_sel_hi:[0,1]
	v_pk_mul_f32 v[22:23], v[140:141], v[22:23] op_sel_hi:[0,1]
	v_pk_mul_f32 v[20:21], v[140:141], v[20:21] op_sel_hi:[0,1]
	v_pk_mul_f32 v[18:19], v[140:141], v[18:19] op_sel_hi:[0,1]
	v_pk_mul_f32 v[16:17], v[140:141], v[16:17] op_sel_hi:[0,1]

.Lattn2_nomask:
	s_add_i32 s9, s34, 0x10000
	s_and_b32 s33, s9, 0x18000
	s_and_b32 s10, s34, 0x18000
	v_add_u32_e32 v239, s33, v237
	v_add_u32_e32 v250, v239, v230
	ds_read_b128 v[128:131], v250 offset:16384
	ds_read_b128 v[132:135], v250 offset:20480
	ds_read_b128 v[136:139], v250 offset:24576
	ds_read_b128 v[140:143], v250 offset:28672
	v_add_u32_e32 v251, s10, v236
	v_add_u32_e32 v250, v251, v230
	ds_read_b128 v[144:147], v250
	ds_read_b128 v[148:151], v250 offset:4096
	v_add_u32_e32 v250, v251, v233
	ds_read_b128 v[152:155], v250
	ds_read_b128 v[156:159], v250 offset:4096
	s_add_i32 s0, s74, s64
	s_addk_i32 s0, 0xc0
	s_mul_i32 s0, s0, s14
	s_add_i32 s0, s0, s92
	s_addk_i32 s0, 0x1c00
	s_add_u32 s98, s82, s0
	s_addc_u32 s99, s83, 0
	s_lshl_b32 s1, s17, 13
	s_add_u32 s46, s76, s1
	s_addc_u32 s47, s77, 0
	s_add_i32 s0, s34, 0x8000
	s_and_b32 s0, s0, 0x18000
	s_add_i32 s0, s5, s0
	s_mov_b32 m0, s0
	s_nop 0
	global_load_lds_dwordx4 v244, s[98:99]
	s_add_i32 m0, s0, 0x2000
	s_add_u32 s98, s98, 0x80
	s_addc_u32 s99, s99, 0
	global_load_lds_dwordx4 v244, s[98:99]
	s_add_i32 m0, s0, 0x4000
	s_nop 0
	global_load_lds_dwordx4 v245, s[46:47]
	s_add_i32 m0, s0, 0x6000
	s_add_u32 s46, s46, 0x80000
	s_addc_u32 s47, s47, 0
	global_load_lds_dwordx4 v245, s[46:47]
	v_max3_f32 v246, v64, v65, v66
	v_max3_f32 v247, v72, v73, v74
	v_max3_f32 v248, v80, v81, v82
	v_max3_f32 v249, v88, v89, v90
	v_max3_f32 v246, v246, v67, v68
	v_max3_f32 v247, v247, v75, v76
	v_max3_f32 v248, v248, v83, v84
	v_max3_f32 v249, v249, v91, v92
	s_waitcnt lgkmcnt(7)
	v_mfma_f32_32x32x16_bf16 v[0:15], v[128:131], v[96:99], v[0:15]
	v_max3_f32 v246, v246, v69, v70
	v_max3_f32 v247, v247, v77, v78
	v_max3_f32 v248, v248, v85, v86
	v_max3_f32 v249, v249, v93, v94
	v_max3_f32 v246, v246, v71, v247
	v_max3_f32 v247, v248, v87, v249
	s_waitcnt lgkmcnt(6)
	v_mfma_f32_32x32x16_bf16 v[48:63], v[132:135], v[96:99], v[48:63]
	v_max3_f32 v246, v246, v79, v95
	v_max3_f32 v246, v246, v247, v247
	v_mov_b32_e32 v247, v246
	s_waitcnt lgkmcnt(5)
	v_mfma_f32_32x32x16_bf16 v[32:47], v[136:139], v[96:99], v[32:47]
	s_waitcnt lgkmcnt(4)
	v_mfma_f32_32x32x16_bf16 v[16:31], v[140:143], v[96:99], v[16:31]
	v_permlane32_swap_b32_e32 v246, v247
	v_max3_f32 v246, v246, v247, v247
	v_max_f32_e32 v251, v214, v246
	v_sub_f32_e32 v247, v214, v251
	v_exp_f32_e32 v250, v247
	v_add_f32_e32 v247, 0x41000000, v214
	v_cmp_gt_f32_e32 vcc, v246, v247
	s_cmp_eq_u64 vcc, 0
	v_mul_f32_e32 v246, v100, v250
	s_cselect_b64 s[0:1], -1, 0
	v_cndmask_b32_e64 v194, v246, v100, s[0:1]
	v_cndmask_b32_e64 v214, v251, v214, s[0:1]
	v_sub_f32_e32 v140, v92, v214
	v_sub_f32_e32 v141, v93, v214
	v_sub_f32_e32 v138, v90, v214
	v_sub_f32_e32 v139, v91, v214
	s_waitcnt lgkmcnt(3)
	v_mfma_f32_32x32x16_bf16 v[96:111], v[144:147], v[160:163], 0
	v_sub_f32_e32 v142, v94, v214
	v_sub_f32_e32 v143, v95, v214
	v_sub_f32_e32 v92, v80, v214
	v_sub_f32_e32 v93, v81, v214
	v_sub_f32_e32 v128, v82, v214
	v_sub_f32_e32 v129, v83, v214
	s_waitcnt lgkmcnt(2)
	v_mfma_f32_32x32x16_bf16 v[112:127], v[148:151], v[160:163], 0
	v_sub_f32_e32 v130, v68, v214
	v_sub_f32_e32 v131, v69, v214
	v_sub_f32_e32 v90, v64, v214
	v_sub_f32_e32 v91, v65, v214
	v_sub_f32_e32 v132, v84, v214
	v_sub_f32_e32 v133, v85, v214
	s_waitcnt lgkmcnt(1)
	v_mfma_f32_32x32x16_bf16 v[96:111], v[152:155], v[164:167], v[96:111]
	v_sub_f32_e32 v94, v66, v214
	v_sub_f32_e32 v95, v67, v214
	v_sub_f32_e32 v134, v86, v214
	v_sub_f32_e32 v135, v87, v214
	v_sub_f32_e32 v136, v88, v214
	v_sub_f32_e32 v137, v89, v214
	s_waitcnt lgkmcnt(0)
	v_mfma_f32_32x32x16_bf16 v[112:127], v[156:159], v[164:167], v[112:127]
	v_sub_f32_e32 v144, v70, v214
	v_sub_f32_e32 v145, v71, v214
	v_sub_f32_e32 v148, v74, v214
	v_sub_f32_e32 v149, v75, v214
	v_sub_f32_e32 v150, v76, v214
	v_sub_f32_e32 v151, v77, v214
	v_sub_f32_e32 v146, v72, v214
	v_sub_f32_e32 v147, v73, v214
	v_sub_f32_e32 v152, v78, v214
	v_sub_f32_e32 v153, v79, v214
	v_mov_b32_e32 v68, v250
	s_branch .Lattn_body_2

.LBB0_866:
	s_add_i32 s10, s35, 2
	s_cmp_ge_u32 s10, s18
	s_cselect_b64 s[90:91], -1, 0
	s_and_b64 vcc, exec, s[90:91]
	s_add_i32 s0, s74, s64
	s_addk_i32 s0, 0x100
	s_mul_i32 s0, s0, s14
	s_add_i32 s0, s0, s92
	s_addk_i32 s0, 0x1c00
	s_add_u32 s98, s82, s0
	s_addc_u32 s99, s83, 0
	s_lshl_b32 s1, s17, 13
	s_add_u32 s0, s76, s1
	s_addc_u32 s1, s77, 0
	s_add_u32 s0, s0, 0x80
	s_addc_u32 s1, s1, 0
	s_add_i32 s32, s5, s33
	s_mov_b32 m0, s32
	s_waitcnt vmcnt(2)
	s_barrier
	s_cbranch_vccnz .LBB0_868
	global_load_lds_dwordx4 v244, s[98:99]
	s_add_i32 m0, s32, 0x2000
	s_add_u32 s98, s98, 0x80
	s_addc_u32 s99, s99, 0
	global_load_lds_dwordx4 v244, s[98:99]
	s_add_i32 m0, s32, 0x4000
	s_nop 0
	global_load_lds_dwordx4 v245, s[0:1]
	s_add_i32 m0, s32, 0x6000
	s_add_u32 s0, s0, 0x80000
	s_addc_u32 s1, s1, 0
	global_load_lds_dwordx4 v245, s[0:1]

.LBB0_870:
	s_add_i32 s0, s34, 0xffff8000
	s_and_b32 s33, s0, 0x18000
	v_add_u32_e32 v76, s33, v237
	v_add_u32_e32 v76, v76, v230
	ds_read_b128 v[80:83], v76 offset:16384
	ds_read_b128 v[84:87], v76 offset:20480
	ds_read_b128 v[88:91], v76 offset:24576
	ds_read_b128 v[92:95], v76 offset:28672
	v_max3_f32 v68, v96, v97, v98
	v_max3_f32 v70, v104, v105, v106
	v_max3_f32 v71, v112, v113, v114
	v_max3_f32 v72, v120, v121, v122
	v_max3_f32 v68, v68, v99, v100
	v_max3_f32 v70, v70, v107, v108
	v_max3_f32 v71, v71, v115, v116
	v_max3_f32 v72, v72, v123, v124
	s_waitcnt lgkmcnt(3)
	v_mfma_f32_32x32x16_bf16 v[0:15], v[80:83], v[64:67], v[0:15]
	v_max3_f32 v68, v68, v101, v102
	v_max3_f32 v70, v70, v109, v110
	v_max3_f32 v71, v71, v117, v118
	v_max3_f32 v72, v72, v125, v126
	s_xor_b32 s34, s33, 0x10000
	v_max3_f32 v68, v68, v103, v70
	v_max3_f32 v70, v71, v119, v72
	s_waitcnt lgkmcnt(2)
	v_mfma_f32_32x32x16_bf16 v[48:63], v[84:87], v[64:67], v[48:63]
	v_max3_f32 v68, v68, v111, v127
	v_max3_f32 v68, v68, v70, v70
	v_mov_b32_e32 v70, v68
	s_waitcnt lgkmcnt(1)
	v_mfma_f32_32x32x16_bf16 v[32:47], v[88:91], v[64:67], v[32:47]
	s_waitcnt lgkmcnt(0)
	v_mfma_f32_32x32x16_bf16 v[16:31], v[92:95], v[64:67], v[16:31]
	v_permlane32_swap_b32_e32 v68, v70
	v_max3_f32 v68, v68, v70, v70
	v_max_f32_e32 v141, v214, v68
	v_sub_f32_e32 v70, v214, v141
	v_exp_f32_e32 v140, v70
	v_add_f32_e32 v70, 0x41000000, v214
	v_cmp_gt_f32_e32 vcc, v68, v70
	s_cmp_eq_u64 vcc, 0
	v_mul_f32_e32 v68, v69, v140
	s_cselect_b64 s[0:1], -1, 0
	v_cndmask_b32_e64 v194, v68, v69, s[0:1]
	v_add_u32_e32 v182, s33, v237
	v_add_u32_e32 v158, s34, v236
	v_add_u32_e32 v88, v158, v233
	v_add_u32_e32 v150, v182, v233
	v_add_u32_e32 v159, v158, v232
	v_cndmask_b32_e64 v214, v141, v214, s[0:1]
	v_add_u32_e32 v141, v182, v232
	v_sub_f32_e32 v180, v102, v214
	v_sub_f32_e32 v181, v103, v214
	v_sub_f32_e32 v116, v116, v214
	v_sub_f32_e32 v117, v117, v214
	v_sub_f32_e32 v108, v108, v214
	v_sub_f32_e32 v109, v109, v214
	v_sub_f32_e32 v124, v124, v214
	v_sub_f32_e32 v125, v125, v214
	v_exp_f32_e32 v116, v116
	v_exp_f32_e32 v117, v117
	v_exp_f32_e32 v108, v108
	v_exp_f32_e32 v124, v124
	v_exp_f32_e32 v109, v109
	v_add_u32_e32 v68, v158, v230
	v_add_u32_e32 v158, v158, v231
	v_exp_f32_e32 v125, v125
	v_sub_f32_e32 v114, v114, v214
	v_sub_f32_e32 v115, v115, v214
	v_sub_f32_e32 v118, v118, v214
	v_sub_f32_e32 v119, v119, v214
	v_sub_f32_e32 v122, v122, v214
	v_sub_f32_e32 v123, v123, v214
	v_sub_f32_e32 v110, v110, v214
	v_sub_f32_e32 v111, v111, v214
	ds_read_b128 v[64:67], v68
	ds_read_b128 v[80:83], v68 offset:4096
	ds_read_b128 v[84:87], v88
	ds_read_b128 v[142:145], v88 offset:4096
	v_sub_f32_e32 v126, v126, v214
	v_sub_f32_e32 v127, v127, v214
	v_sub_f32_e32 v106, v106, v214
	v_sub_f32_e32 v107, v107, v214
	v_exp_f32_e32 v114, v114
	v_exp_f32_e32 v115, v115
	v_exp_f32_e32 v118, v118
	s_waitcnt lgkmcnt(0)
	v_mfma_f32_32x32x16_bf16 v[64:79], v[64:67], v[160:163], 0
	v_exp_f32_e32 v119, v119
	v_exp_f32_e32 v122, v122
	v_exp_f32_e32 v123, v123
	v_exp_f32_e32 v110, v110
	v_exp_f32_e32 v126, v126
	v_exp_f32_e32 v111, v111
	v_exp_f32_e32 v127, v127
	v_mfma_f32_32x32x16_bf16 v[64:79], v[84:87], v[164:167], v[64:79]
	v_sub_f32_e32 v104, v104, v214
	v_sub_f32_e32 v105, v105, v214
	v_sub_f32_e32 v112, v112, v214
	v_sub_f32_e32 v113, v113, v214
	v_sub_f32_e32 v120, v120, v214
	v_sub_f32_e32 v121, v121, v214
	v_cvt_pk_bf16_f32 v183, v118, v119
	v_exp_f32_e32 v112, v112
	v_exp_f32_e32 v113, v113
	v_exp_f32_e32 v120, v120
	v_mfma_f32_32x32x16_bf16 v[80:95], v[80:83], v[160:163], 0
	v_exp_f32_e32 v121, v121
	v_cvt_pk_bf16_f32 v186, v108, v109
	v_cvt_pk_bf16_f32 v187, v110, v111
	v_mfma_f32_32x32x16_bf16 v[80:95], v[142:145], v[164:167], v[80:95]
	ds_read_b128 v[142:145], v150 offset:16384
	ds_read_b128 v[146:149], v150 offset:20480
	s_waitcnt lgkmcnt(0)
	v_mfma_f32_32x32x16_bf16 v[0:15], v[142:145], v[136:139], v[0:15]
	ds_read_b128 v[142:145], v150 offset:24576
	ds_read_b128 v[150:153], v150 offset:28672
	ds_read_b128 v[154:157], v159
	ds_read_b128 v[176:179], v159 offset:4096
	v_mfma_f32_32x32x16_bf16 v[48:63], v[146:149], v[136:139], v[48:63]
	ds_read_b128 v[146:149], v158
	ds_read_b128 v[238:241], v158 offset:4096
	v_sub_f32_e32 v158, v96, v214
	v_sub_f32_e32 v159, v97, v214
	s_waitcnt lgkmcnt(0)
	v_mfma_f32_32x32x16_bf16 v[32:47], v[142:145], v[136:139], v[32:47]
	v_sub_f32_e32 v142, v98, v214
	v_sub_f32_e32 v143, v99, v214
	v_sub_f32_e32 v144, v100, v214
	v_sub_f32_e32 v145, v101, v214
	ds_read_b128 v[96:99], v141 offset:16384
	ds_read_b128 v[100:103], v141 offset:20480
	s_waitcnt lgkmcnt(0)
	v_mfma_f32_32x32x16_bf16 v[0:15], v[96:99], v[132:135], v[0:15]
	ds_read_b128 v[96:99], v141 offset:24576
	v_mfma_f32_32x32x16_bf16 v[48:63], v[100:103], v[132:135], v[48:63]
	ds_read_b128 v[100:103], v141 offset:28672
	v_add_u32_e32 v141, v182, v231
	v_cvt_pk_bf16_f32 v182, v116, v117
	v_mfma_f32_32x32x16_bf16 v[16:31], v[150:153], v[136:139], v[16:31]
	v_exp_f32_e32 v138, v142
	v_exp_f32_e32 v139, v143
	v_exp_f32_e32 v142, v144
	v_exp_f32_e32 v143, v145
	v_exp_f32_e32 v144, v180
	v_exp_f32_e32 v145, v181
	v_exp_f32_e32 v136, v158
	s_waitcnt lgkmcnt(0)
	v_mfma_f32_32x32x16_bf16 v[32:47], v[96:99], v[132:135], v[32:47]
	ds_read_b128 v[96:99], v141 offset:16384
	v_exp_f32_e32 v137, v159
	v_cvt_pk_bf16_f32 v180, v112, v113
	v_cvt_pk_bf16_f32 v181, v114, v115
	v_add_f32_e32 v152, v136, v112
	v_add_f32_e32 v153, v137, v113
	v_mfma_f32_32x32x16_bf16 v[16:31], v[100:103], v[132:135], v[16:31]
	v_add_f32_e64 v100, v108, v124
	v_add_f32_e64 v101, v109, v125
	v_add_f32_e64 v102, v142, v116
	v_add_f32_e64 v103, v143, v117
	v_exp_f32_e32 v134, v106
	v_exp_f32_e32 v135, v107
	v_exp_f32_e32 v132, v104
	v_exp_f32_e32 v133, v105
	v_add_f32_e32 v106, v138, v114
	v_add_f32_e32 v107, v139, v115
	v_mfma_f32_32x32x16_bf16 v[64:79], v[154:157], v[168:171], v[64:79]
	v_add_f32_e64 v154, v102, v100
	v_add_f32_e64 v155, v103, v101
	ds_read_b128 v[100:103], v141 offset:20480
	v_add_f32_e64 v104, v134, v122
	v_add_f32_e64 v105, v135, v123
	v_add_f32_e32 v150, v132, v120
	v_add_f32_e32 v151, v133, v121
	v_add_f32_e32 v104, v106, v104
	v_add_f32_e32 v105, v107, v105
	v_cvt_pk_bf16_f32 v184, v132, v133
	v_cvt_pk_bf16_f32 v185, v134, v135
	v_mfma_f32_32x32x16_bf16 v[64:79], v[146:149], v[172:175], v[64:79]
	v_add_f32_e64 v146, v110, v126
	v_add_f32_e64 v147, v111, v127
	v_add_f32_e64 v148, v144, v118
	v_add_f32_e64 v149, v145, v119
	s_waitcnt lgkmcnt(0)
	v_mfma_f32_32x32x16_bf16 v[0:15], v[96:99], v[128:131], v[0:15]
	v_add_f32_e64 v98, v148, v146
	v_add_f32_e64 v99, v149, v147
	v_add_f32_e64 v96, v152, v150
	v_add_f32_e64 v97, v153, v151
	v_add_f32_e64 v98, v104, v98
	v_add_f32_e64 v99, v105, v99
	ds_read_b128 v[104:107], v141 offset:24576
	v_add_f32_e32 v96, v96, v154
	v_add_f32_e32 v97, v97, v155
	s_nop 0
	v_add_f32_e32 v96, v96, v97
	v_mfma_f32_32x32x16_bf16 v[48:63], v[100:103], v[128:131], v[48:63]
	ds_read_b128 v[100:103], v141 offset:28672
	v_add_f32_e32 v97, v98, v99
	v_add_f32_e32 v146, v96, v97
	v_cvt_pk_bf16_f32 v96, v136, v137
	v_cvt_pk_bf16_f32 v97, v138, v139
	v_cvt_pk_bf16_f32 v98, v142, v143
	v_cvt_pk_bf16_f32 v99, v144, v145
	v_mfma_f32_32x32x16_bf16 v[80:95], v[176:179], v[168:171], v[80:95]
	v_cvt_pk_bf16_f32 v176, v120, v121
	v_cvt_pk_bf16_f32 v177, v122, v123
	v_cvt_pk_bf16_f32 v178, v124, v125
	v_cvt_pk_bf16_f32 v179, v126, v127
	s_waitcnt lgkmcnt(0)
	v_mfma_f32_32x32x16_bf16 v[32:47], v[104:107], v[128:131], v[32:47]
	v_mfma_f32_32x32x16_bf16 v[16:31], v[100:103], v[128:131], v[16:31]
	v_add_f32_e32 v100, v194, v146
	v_mfma_f32_32x32x16_bf16 v[80:95], v[238:241], v[172:175], v[80:95]
	s_cbranch_vccz .LBB0_872
	v_pk_mul_f32 v[14:15], v[140:141], v[14:15] op_sel_hi:[0,1]
	v_pk_mul_f32 v[12:13], v[140:141], v[12:13] op_sel_hi:[0,1]
	v_pk_mul_f32 v[10:11], v[140:141], v[10:11] op_sel_hi:[0,1]
	v_pk_mul_f32 v[8:9], v[140:141], v[8:9] op_sel_hi:[0,1]
	v_pk_mul_f32 v[6:7], v[140:141], v[6:7] op_sel_hi:[0,1]
	v_pk_mul_f32 v[4:5], v[140:141], v[4:5] op_sel_hi:[0,1]
	v_pk_mul_f32 v[2:3], v[140:141], v[2:3] op_sel_hi:[0,1]
	v_pk_mul_f32 v[0:1], v[140:141], v[0:1] op_sel_hi:[0,1]
	v_pk_mul_f32 v[62:63], v[140:141], v[62:63] op_sel_hi:[0,1]
	v_pk_mul_f32 v[60:61], v[140:141], v[60:61] op_sel_hi:[0,1]
	v_pk_mul_f32 v[58:59], v[140:141], v[58:59] op_sel_hi:[0,1]
	v_pk_mul_f32 v[56:57], v[140:141], v[56:57] op_sel_hi:[0,1]
	v_pk_mul_f32 v[54:55], v[140:141], v[54:55] op_sel_hi:[0,1]
	v_pk_mul_f32 v[52:53], v[140:141], v[52:53] op_sel_hi:[0,1]
	v_pk_mul_f32 v[50:51], v[140:141], v[50:51] op_sel_hi:[0,1]
	v_pk_mul_f32 v[48:49], v[140:141], v[48:49] op_sel_hi:[0,1]
	v_pk_mul_f32 v[46:47], v[140:141], v[46:47] op_sel_hi:[0,1]
	v_pk_mul_f32 v[44:45], v[140:141], v[44:45] op_sel_hi:[0,1]
	v_pk_mul_f32 v[42:43], v[140:141], v[42:43] op_sel_hi:[0,1]
	v_pk_mul_f32 v[40:41], v[140:141], v[40:41] op_sel_hi:[0,1]
	v_pk_mul_f32 v[38:39], v[140:141], v[38:39] op_sel_hi:[0,1]
	v_pk_mul_f32 v[36:37], v[140:141], v[36:37] op_sel_hi:[0,1]
	v_pk_mul_f32 v[34:35], v[140:141], v[34:35] op_sel_hi:[0,1]
	v_pk_mul_f32 v[32:33], v[140:141], v[32:33] op_sel_hi:[0,1]
	v_pk_mul_f32 v[30:31], v[140:141], v[30:31] op_sel_hi:[0,1]
	v_pk_mul_f32 v[28:29], v[140:141], v[28:29] op_sel_hi:[0,1]
	v_pk_mul_f32 v[26:27], v[140:141], v[26:27] op_sel_hi:[0,1]
	v_pk_mul_f32 v[24:25], v[140:141], v[24:25] op_sel_hi:[0,1]
	v_pk_mul_f32 v[22:23], v[140:141], v[22:23] op_sel_hi:[0,1]
	v_pk_mul_f32 v[20:21], v[140:141], v[20:21] op_sel_hi:[0,1]
	v_pk_mul_f32 v[18:19], v[140:141], v[18:19] op_sel_hi:[0,1]
	v_pk_mul_f32 v[16:17], v[140:141], v[16:17] op_sel_hi:[0,1]
